# MoE token sort: the wave's 16 gathered rows converted in two batches with all loads of a batch in flight (destinations read from LDS up front)
# baseline (speedup 1.0000x reference)
; __device__ __forceinline__ float bf_lo(unsigned w) { return __uint_as_float(w << 16); }
; __device__ __forceinline__ float bf_hi(unsigned w) { return __uint_as_float(w & 0xffff0000u); }
; #define LAS __attribute__((address_space(3)))
; template <int l, int SEL> __device__ __forceinline__ void layer_body(const Args& args, LAS unsigned char* ldsp, unsigned char* lds, const int G, const int bx, const int vcu, const int wv) {
;     ...
;                     for (int sidx = wave; sidx < 128; sidx += NWAVES) { const int p = ((LAS int*)ldsp)[64 + sidx]; const int tk = tb + (sidx >> 1);
;                         { const v4u a = *(const v4u*)(q_hb + (size_t)tk * 1024 + 16 * lane), b = *(const v4u*)(q_hb + (size_t)tk * 1024 + 16 * lane + 8); v4u o; int w;
;                             w = 0; w = __builtin_amdgcn_cvt_pk_fp8_f32(pg8::bf_lo(a.x), pg8::bf_hi(a.x), w, false); w = __builtin_amdgcn_cvt_pk_fp8_f32(pg8::bf_lo(a.y), pg8::bf_hi(a.y), w, true); o.x = (unsigned)w;
;                             w = 0; w = __builtin_amdgcn_cvt_pk_fp8_f32(pg8::bf_lo(a.z), pg8::bf_hi(a.z), w, false); w = __builtin_amdgcn_cvt_pk_fp8_f32(pg8::bf_lo(a.w), pg8::bf_hi(a.w), w, true); o.y = (unsigned)w;
;                             w = 0; w = __builtin_amdgcn_cvt_pk_fp8_f32(pg8::bf_lo(b.x), pg8::bf_hi(b.x), w, false); w = __builtin_amdgcn_cvt_pk_fp8_f32(pg8::bf_lo(b.y), pg8::bf_hi(b.y), w, true); o.z = (unsigned)w;
;                             w = 0; w = __builtin_amdgcn_cvt_pk_fp8_f32(pg8::bf_lo(b.z), pg8::bf_hi(b.z), w, false); w = __builtin_amdgcn_cvt_pk_fp8_f32(pg8::bf_lo(b.w), pg8::bf_hi(b.w), w, true); o.w = (unsigned)w;
;                             *(v4u*)((unsigned char*)q_Xs + (size_t)p * 1024 + 16 * lane) = o; } }
.LBB0_1977:
	s_mov_b64 s[26:27], s[0:1]
	s_load_dwordx2 s[26:27], s[26:27], 0xc0
	v_mov_b32_e32 v57, s24
	ds_read_b32 v32, v57
	ds_read_b32 v33, v57 offset:32
	ds_read_b32 v34, v57 offset:64
	ds_read_b32 v35, v57 offset:96
	ds_read_b32 v36, v57 offset:128
	ds_read_b32 v37, v57 offset:160
	ds_read_b32 v38, v57 offset:192
	ds_read_b32 v39, v57 offset:224
	ds_read_b32 v40, v57 offset:256
	ds_read_b32 v41, v57 offset:288
	ds_read_b32 v42, v57 offset:320
	ds_read_b32 v43, v57 offset:352
	ds_read_b32 v44, v57 offset:384
	ds_read_b32 v45, v57 offset:416
	ds_read_b32 v46, v57 offset:448
	ds_read_b32 v47, v57 offset:480
	s_waitcnt lgkmcnt(0)
	s_add_i32 s28, s16, 0
	s_ashr_i32 s29, s28, 31
	s_lshl_b64 s[38:39], s[28:29], 11
	s_add_u32 s38, s26, s38
	s_addc_u32 s39, s27, s39
	v_lshl_add_u64 v[48:49], s[38:39], 0, v[0:1]
	v_add_co_u32_e32 v48, vcc, s23, v48
	s_nop 1
	v_addc_co_u32_e32 v49, vcc, 0, v49, vcc
	global_load_dwordx4 v[64:67], v[48:49], off
	global_load_dwordx4 v[68:71], v[48:49], off offset:16
	s_add_i32 s28, s16, 4
	s_ashr_i32 s29, s28, 31
	s_lshl_b64 s[38:39], s[28:29], 11
	s_add_u32 s38, s26, s38
	s_addc_u32 s39, s27, s39
	v_lshl_add_u64 v[48:49], s[38:39], 0, v[0:1]
	v_add_co_u32_e32 v48, vcc, s23, v48
	s_nop 1
	v_addc_co_u32_e32 v49, vcc, 0, v49, vcc
	global_load_dwordx4 v[72:75], v[48:49], off
	global_load_dwordx4 v[76:79], v[48:49], off offset:16
	s_add_i32 s28, s16, 8
	s_ashr_i32 s29, s28, 31
	s_lshl_b64 s[38:39], s[28:29], 11
	s_add_u32 s38, s26, s38
	s_addc_u32 s39, s27, s39
	v_lshl_add_u64 v[48:49], s[38:39], 0, v[0:1]
	v_add_co_u32_e32 v48, vcc, s23, v48
	s_nop 1
	v_addc_co_u32_e32 v49, vcc, 0, v49, vcc
	global_load_dwordx4 v[80:83], v[48:49], off
	global_load_dwordx4 v[84:87], v[48:49], off offset:16
	s_add_i32 s28, s16, 12
	s_ashr_i32 s29, s28, 31
	s_lshl_b64 s[38:39], s[28:29], 11
	s_add_u32 s38, s26, s38
	s_addc_u32 s39, s27, s39
	v_lshl_add_u64 v[48:49], s[38:39], 0, v[0:1]
	v_add_co_u32_e32 v48, vcc, s23, v48
	s_nop 1
	v_addc_co_u32_e32 v49, vcc, 0, v49, vcc
	global_load_dwordx4 v[88:91], v[48:49], off
	global_load_dwordx4 v[92:95], v[48:49], off offset:16
	s_add_i32 s28, s16, 16
	s_ashr_i32 s29, s28, 31
	s_lshl_b64 s[38:39], s[28:29], 11
	s_add_u32 s38, s26, s38
	s_addc_u32 s39, s27, s39
	v_lshl_add_u64 v[48:49], s[38:39], 0, v[0:1]
	v_add_co_u32_e32 v48, vcc, s23, v48
	s_nop 1
	v_addc_co_u32_e32 v49, vcc, 0, v49, vcc
	global_load_dwordx4 v[96:99], v[48:49], off
	global_load_dwordx4 v[100:103], v[48:49], off offset:16
	s_add_i32 s28, s16, 20
	s_ashr_i32 s29, s28, 31
	s_lshl_b64 s[38:39], s[28:29], 11
	s_add_u32 s38, s26, s38
	s_addc_u32 s39, s27, s39
	v_lshl_add_u64 v[48:49], s[38:39], 0, v[0:1]
	v_add_co_u32_e32 v48, vcc, s23, v48
	s_nop 1
	v_addc_co_u32_e32 v49, vcc, 0, v49, vcc
	global_load_dwordx4 v[104:107], v[48:49], off
	global_load_dwordx4 v[108:111], v[48:49], off offset:16
	s_add_i32 s28, s16, 24
	s_ashr_i32 s29, s28, 31
	s_lshl_b64 s[38:39], s[28:29], 11
	s_add_u32 s38, s26, s38
	s_addc_u32 s39, s27, s39
	v_lshl_add_u64 v[48:49], s[38:39], 0, v[0:1]
	v_add_co_u32_e32 v48, vcc, s23, v48
	s_nop 1
	v_addc_co_u32_e32 v49, vcc, 0, v49, vcc
	global_load_dwordx4 v[112:115], v[48:49], off
	global_load_dwordx4 v[116:119], v[48:49], off offset:16
	s_add_i32 s28, s16, 28
	s_ashr_i32 s29, s28, 31
	s_lshl_b64 s[38:39], s[28:29], 11
	s_add_u32 s38, s26, s38
	s_addc_u32 s39, s27, s39
	v_lshl_add_u64 v[48:49], s[38:39], 0, v[0:1]
	v_add_co_u32_e32 v48, vcc, s23, v48
	s_nop 1
	v_addc_co_u32_e32 v49, vcc, 0, v49, vcc
	global_load_dwordx4 v[120:123], v[48:49], off
	global_load_dwordx4 v[124:127], v[48:49], off offset:16
	v_mov_b32_e32 v50, v32
	v_ashrrev_i32_e32 v51, 31, v50
	v_lshlrev_b64 v[50:51], 10, v[50:51]
	v_lshl_add_u64 v[50:51], s[26:27], 0, v[50:51]
	v_lshl_add_u64 v[50:51], v[50:51], 0, v[4:5]
	v_add_co_u32_e32 v50, vcc, 0x14500000, v50
	s_nop 1
	v_addc_co_u32_e32 v51, vcc, 0, v51, vcc
	v_mov_b32_e32 v52, 0
	v_mov_b32_e32 v53, 0
	v_mov_b32_e32 v54, 0
	v_mov_b32_e32 v55, 0
	s_waitcnt vmcnt(15)
	v_lshlrev_b32_e32 v56, 16, v64
	v_and_b32_e32 v64, 0xffff0000, v64
	v_cvt_pk_fp8_f32 v52, v56, v64
	v_lshlrev_b32_e32 v56, 16, v65
	v_and_b32_e32 v65, 0xffff0000, v65
	v_cvt_pk_fp8_f32 v52, v56, v65 op_sel:[0,0,1]
	v_lshlrev_b32_e32 v56, 16, v66
	v_and_b32_e32 v66, 0xffff0000, v66
	v_cvt_pk_fp8_f32 v53, v56, v66
	v_lshlrev_b32_e32 v56, 16, v67
	v_and_b32_e32 v67, 0xffff0000, v67
	v_cvt_pk_fp8_f32 v53, v56, v67 op_sel:[0,0,1]
	s_waitcnt vmcnt(14)
	v_lshlrev_b32_e32 v56, 16, v68
	v_and_b32_e32 v68, 0xffff0000, v68
	v_cvt_pk_fp8_f32 v54, v56, v68
	v_lshlrev_b32_e32 v56, 16, v69
	v_and_b32_e32 v69, 0xffff0000, v69
	v_cvt_pk_fp8_f32 v54, v56, v69 op_sel:[0,0,1]
	v_lshlrev_b32_e32 v56, 16, v70
	v_and_b32_e32 v70, 0xffff0000, v70
	v_cvt_pk_fp8_f32 v55, v56, v70
	v_lshlrev_b32_e32 v56, 16, v71
	v_and_b32_e32 v71, 0xffff0000, v71
	v_cvt_pk_fp8_f32 v55, v56, v71 op_sel:[0,0,1]
	global_store_dwordx4 v[50:51], v[52:55], off
	v_mov_b32_e32 v50, v33
	v_ashrrev_i32_e32 v51, 31, v50
	v_lshlrev_b64 v[50:51], 10, v[50:51]
	v_lshl_add_u64 v[50:51], s[26:27], 0, v[50:51]
	v_lshl_add_u64 v[50:51], v[50:51], 0, v[4:5]
	v_add_co_u32_e32 v50, vcc, 0x14500000, v50
	s_nop 1
	v_addc_co_u32_e32 v51, vcc, 0, v51, vcc
	v_mov_b32_e32 v52, 0
	v_mov_b32_e32 v53, 0
	v_mov_b32_e32 v54, 0
	v_mov_b32_e32 v55, 0
	s_waitcnt vmcnt(14)
	v_lshlrev_b32_e32 v56, 16, v72
	v_and_b32_e32 v72, 0xffff0000, v72
	v_cvt_pk_fp8_f32 v52, v56, v72
	v_lshlrev_b32_e32 v56, 16, v73
	v_and_b32_e32 v73, 0xffff0000, v73
	v_cvt_pk_fp8_f32 v52, v56, v73 op_sel:[0,0,1]
	v_lshlrev_b32_e32 v56, 16, v74
	v_and_b32_e32 v74, 0xffff0000, v74
	v_cvt_pk_fp8_f32 v53, v56, v74
	v_lshlrev_b32_e32 v56, 16, v75
	v_and_b32_e32 v75, 0xffff0000, v75
	v_cvt_pk_fp8_f32 v53, v56, v75 op_sel:[0,0,1]
	s_waitcnt vmcnt(13)
; __device__ __forceinline__ float bf_lo(unsigned w) { return __uint_as_float(w << 16); }
; __device__ __forceinline__ float bf_hi(unsigned w) { return __uint_as_float(w & 0xffff0000u); }
; #define LAS __attribute__((address_space(3)))
; template <int l, int SEL> __device__ __forceinline__ void layer_body(const Args& args, LAS unsigned char* ldsp, unsigned char* lds, const int G, const int bx, const int vcu, const int wv) {
;     ...
;                     for (int sidx = wave; sidx < 128; sidx += NWAVES) { const int p = ((LAS int*)ldsp)[64 + sidx]; const int tk = tb + (sidx >> 1);
;                         { const v4u a = *(const v4u*)(q_hb + (size_t)tk * 1024 + 16 * lane), b = *(const v4u*)(q_hb + (size_t)tk * 1024 + 16 * lane + 8); v4u o; int w;
;                             w = 0; w = __builtin_amdgcn_cvt_pk_fp8_f32(pg8::bf_lo(a.x), pg8::bf_hi(a.x), w, false); w = __builtin_amdgcn_cvt_pk_fp8_f32(pg8::bf_lo(a.y), pg8::bf_hi(a.y), w, true); o.x = (unsigned)w;
;                             w = 0; w = __builtin_amdgcn_cvt_pk_fp8_f32(pg8::bf_lo(a.z), pg8::bf_hi(a.z), w, false); w = __builtin_amdgcn_cvt_pk_fp8_f32(pg8::bf_lo(a.w), pg8::bf_hi(a.w), w, true); o.y = (unsigned)w;
;                             w = 0; w = __builtin_amdgcn_cvt_pk_fp8_f32(pg8::bf_lo(b.x), pg8::bf_hi(b.x), w, false); w = __builtin_amdgcn_cvt_pk_fp8_f32(pg8::bf_lo(b.y), pg8::bf_hi(b.y), w, true); o.z = (unsigned)w;
;                             w = 0; w = __builtin_amdgcn_cvt_pk_fp8_f32(pg8::bf_lo(b.z), pg8::bf_hi(b.z), w, false); w = __builtin_amdgcn_cvt_pk_fp8_f32(pg8::bf_lo(b.w), pg8::bf_hi(b.w), w, true); o.w = (unsigned)w;
;                             *(v4u*)((unsigned char*)q_Xs + (size_t)p * 1024 + 16 * lane) = o; } }
	v_lshlrev_b32_e32 v56, 16, v76
	v_and_b32_e32 v76, 0xffff0000, v76
	v_cvt_pk_fp8_f32 v54, v56, v76
	v_lshlrev_b32_e32 v56, 16, v77
	v_and_b32_e32 v77, 0xffff0000, v77
	v_cvt_pk_fp8_f32 v54, v56, v77 op_sel:[0,0,1]
	v_lshlrev_b32_e32 v56, 16, v78
	v_and_b32_e32 v78, 0xffff0000, v78
	v_cvt_pk_fp8_f32 v55, v56, v78
	v_lshlrev_b32_e32 v56, 16, v79
	v_and_b32_e32 v79, 0xffff0000, v79
	v_cvt_pk_fp8_f32 v55, v56, v79 op_sel:[0,0,1]
	global_store_dwordx4 v[50:51], v[52:55], off
	v_mov_b32_e32 v50, v34
	v_ashrrev_i32_e32 v51, 31, v50
	v_lshlrev_b64 v[50:51], 10, v[50:51]
	v_lshl_add_u64 v[50:51], s[26:27], 0, v[50:51]
	v_lshl_add_u64 v[50:51], v[50:51], 0, v[4:5]
	v_add_co_u32_e32 v50, vcc, 0x14500000, v50
	s_nop 1
	v_addc_co_u32_e32 v51, vcc, 0, v51, vcc
	v_mov_b32_e32 v52, 0
	v_mov_b32_e32 v53, 0
	v_mov_b32_e32 v54, 0
	v_mov_b32_e32 v55, 0
	s_waitcnt vmcnt(13)
	v_lshlrev_b32_e32 v56, 16, v80
	v_and_b32_e32 v80, 0xffff0000, v80
	v_cvt_pk_fp8_f32 v52, v56, v80
	v_lshlrev_b32_e32 v56, 16, v81
	v_and_b32_e32 v81, 0xffff0000, v81
	v_cvt_pk_fp8_f32 v52, v56, v81 op_sel:[0,0,1]
	v_lshlrev_b32_e32 v56, 16, v82
	v_and_b32_e32 v82, 0xffff0000, v82
	v_cvt_pk_fp8_f32 v53, v56, v82
	v_lshlrev_b32_e32 v56, 16, v83
	v_and_b32_e32 v83, 0xffff0000, v83
	v_cvt_pk_fp8_f32 v53, v56, v83 op_sel:[0,0,1]
	s_waitcnt vmcnt(12)
	v_lshlrev_b32_e32 v56, 16, v84
	v_and_b32_e32 v84, 0xffff0000, v84
	v_cvt_pk_fp8_f32 v54, v56, v84
	v_lshlrev_b32_e32 v56, 16, v85
	v_and_b32_e32 v85, 0xffff0000, v85
	v_cvt_pk_fp8_f32 v54, v56, v85 op_sel:[0,0,1]
	v_lshlrev_b32_e32 v56, 16, v86
	v_and_b32_e32 v86, 0xffff0000, v86
	v_cvt_pk_fp8_f32 v55, v56, v86
	v_lshlrev_b32_e32 v56, 16, v87
	v_and_b32_e32 v87, 0xffff0000, v87
	v_cvt_pk_fp8_f32 v55, v56, v87 op_sel:[0,0,1]
	global_store_dwordx4 v[50:51], v[52:55], off
	v_mov_b32_e32 v50, v35
	v_ashrrev_i32_e32 v51, 31, v50
	v_lshlrev_b64 v[50:51], 10, v[50:51]
	v_lshl_add_u64 v[50:51], s[26:27], 0, v[50:51]
	v_lshl_add_u64 v[50:51], v[50:51], 0, v[4:5]
	v_add_co_u32_e32 v50, vcc, 0x14500000, v50
	s_nop 1
	v_addc_co_u32_e32 v51, vcc, 0, v51, vcc
	v_mov_b32_e32 v52, 0
	v_mov_b32_e32 v53, 0
	v_mov_b32_e32 v54, 0
	v_mov_b32_e32 v55, 0
	s_waitcnt vmcnt(12)
	v_lshlrev_b32_e32 v56, 16, v88
	v_and_b32_e32 v88, 0xffff0000, v88
	v_cvt_pk_fp8_f32 v52, v56, v88
	v_lshlrev_b32_e32 v56, 16, v89
	v_and_b32_e32 v89, 0xffff0000, v89
	v_cvt_pk_fp8_f32 v52, v56, v89 op_sel:[0,0,1]
	v_lshlrev_b32_e32 v56, 16, v90
	v_and_b32_e32 v90, 0xffff0000, v90
	v_cvt_pk_fp8_f32 v53, v56, v90
	v_lshlrev_b32_e32 v56, 16, v91
	v_and_b32_e32 v91, 0xffff0000, v91
	v_cvt_pk_fp8_f32 v53, v56, v91 op_sel:[0,0,1]
	s_waitcnt vmcnt(11)
	v_lshlrev_b32_e32 v56, 16, v92
	v_and_b32_e32 v92, 0xffff0000, v92
	v_cvt_pk_fp8_f32 v54, v56, v92
	v_lshlrev_b32_e32 v56, 16, v93
	v_and_b32_e32 v93, 0xffff0000, v93
	v_cvt_pk_fp8_f32 v54, v56, v93 op_sel:[0,0,1]
	v_lshlrev_b32_e32 v56, 16, v94
	v_and_b32_e32 v94, 0xffff0000, v94
	v_cvt_pk_fp8_f32 v55, v56, v94
	v_lshlrev_b32_e32 v56, 16, v95
	v_and_b32_e32 v95, 0xffff0000, v95
	v_cvt_pk_fp8_f32 v55, v56, v95 op_sel:[0,0,1]
	global_store_dwordx4 v[50:51], v[52:55], off
	v_mov_b32_e32 v50, v36
	v_ashrrev_i32_e32 v51, 31, v50
	v_lshlrev_b64 v[50:51], 10, v[50:51]
	v_lshl_add_u64 v[50:51], s[26:27], 0, v[50:51]
	v_lshl_add_u64 v[50:51], v[50:51], 0, v[4:5]
	v_add_co_u32_e32 v50, vcc, 0x14500000, v50
	s_nop 1
	v_addc_co_u32_e32 v51, vcc, 0, v51, vcc
	v_mov_b32_e32 v52, 0
	v_mov_b32_e32 v53, 0
	v_mov_b32_e32 v54, 0
	v_mov_b32_e32 v55, 0
	s_waitcnt vmcnt(11)
	v_lshlrev_b32_e32 v56, 16, v96
	v_and_b32_e32 v96, 0xffff0000, v96
	v_cvt_pk_fp8_f32 v52, v56, v96
	v_lshlrev_b32_e32 v56, 16, v97
	v_and_b32_e32 v97, 0xffff0000, v97
	v_cvt_pk_fp8_f32 v52, v56, v97 op_sel:[0,0,1]
	v_lshlrev_b32_e32 v56, 16, v98
	v_and_b32_e32 v98, 0xffff0000, v98
	v_cvt_pk_fp8_f32 v53, v56, v98
	v_lshlrev_b32_e32 v56, 16, v99
	v_and_b32_e32 v99, 0xffff0000, v99
	v_cvt_pk_fp8_f32 v53, v56, v99 op_sel:[0,0,1]
	s_waitcnt vmcnt(10)
	v_lshlrev_b32_e32 v56, 16, v100
	v_and_b32_e32 v100, 0xffff0000, v100
	v_cvt_pk_fp8_f32 v54, v56, v100
	v_lshlrev_b32_e32 v56, 16, v101
	v_and_b32_e32 v101, 0xffff0000, v101
	v_cvt_pk_fp8_f32 v54, v56, v101 op_sel:[0,0,1]
	v_lshlrev_b32_e32 v56, 16, v102
	v_and_b32_e32 v102, 0xffff0000, v102
	v_cvt_pk_fp8_f32 v55, v56, v102
	v_lshlrev_b32_e32 v56, 16, v103
	v_and_b32_e32 v103, 0xffff0000, v103
	v_cvt_pk_fp8_f32 v55, v56, v103 op_sel:[0,0,1]
	global_store_dwordx4 v[50:51], v[52:55], off
	v_mov_b32_e32 v50, v37
	v_ashrrev_i32_e32 v51, 31, v50
	v_lshlrev_b64 v[50:51], 10, v[50:51]
	v_lshl_add_u64 v[50:51], s[26:27], 0, v[50:51]
	v_lshl_add_u64 v[50:51], v[50:51], 0, v[4:5]
	v_add_co_u32_e32 v50, vcc, 0x14500000, v50
	s_nop 1
	v_addc_co_u32_e32 v51, vcc, 0, v51, vcc
	v_mov_b32_e32 v52, 0
	v_mov_b32_e32 v53, 0
	v_mov_b32_e32 v54, 0
	v_mov_b32_e32 v55, 0
	s_waitcnt vmcnt(10)
	v_lshlrev_b32_e32 v56, 16, v104
	v_and_b32_e32 v104, 0xffff0000, v104
	v_cvt_pk_fp8_f32 v52, v56, v104
	v_lshlrev_b32_e32 v56, 16, v105
	v_and_b32_e32 v105, 0xffff0000, v105
	v_cvt_pk_fp8_f32 v52, v56, v105 op_sel:[0,0,1]
	v_lshlrev_b32_e32 v56, 16, v106
	v_and_b32_e32 v106, 0xffff0000, v106
	v_cvt_pk_fp8_f32 v53, v56, v106
	v_lshlrev_b32_e32 v56, 16, v107
	v_and_b32_e32 v107, 0xffff0000, v107
	v_cvt_pk_fp8_f32 v53, v56, v107 op_sel:[0,0,1]
	s_waitcnt vmcnt(9)
; __device__ __forceinline__ float bf_lo(unsigned w) { return __uint_as_float(w << 16); }
; __device__ __forceinline__ float bf_hi(unsigned w) { return __uint_as_float(w & 0xffff0000u); }
; #define LAS __attribute__((address_space(3)))
; template <int l, int SEL> __device__ __forceinline__ void layer_body(const Args& args, LAS unsigned char* ldsp, unsigned char* lds, const int G, const int bx, const int vcu, const int wv) {
;     ...
;                     for (int sidx = wave; sidx < 128; sidx += NWAVES) { const int p = ((LAS int*)ldsp)[64 + sidx]; const int tk = tb + (sidx >> 1);
;                         { const v4u a = *(const v4u*)(q_hb + (size_t)tk * 1024 + 16 * lane), b = *(const v4u*)(q_hb + (size_t)tk * 1024 + 16 * lane + 8); v4u o; int w;
;                             w = 0; w = __builtin_amdgcn_cvt_pk_fp8_f32(pg8::bf_lo(a.x), pg8::bf_hi(a.x), w, false); w = __builtin_amdgcn_cvt_pk_fp8_f32(pg8::bf_lo(a.y), pg8::bf_hi(a.y), w, true); o.x = (unsigned)w;
;                             w = 0; w = __builtin_amdgcn_cvt_pk_fp8_f32(pg8::bf_lo(a.z), pg8::bf_hi(a.z), w, false); w = __builtin_amdgcn_cvt_pk_fp8_f32(pg8::bf_lo(a.w), pg8::bf_hi(a.w), w, true); o.y = (unsigned)w;
;                             w = 0; w = __builtin_amdgcn_cvt_pk_fp8_f32(pg8::bf_lo(b.x), pg8::bf_hi(b.x), w, false); w = __builtin_amdgcn_cvt_pk_fp8_f32(pg8::bf_lo(b.y), pg8::bf_hi(b.y), w, true); o.z = (unsigned)w;
;                             w = 0; w = __builtin_amdgcn_cvt_pk_fp8_f32(pg8::bf_lo(b.z), pg8::bf_hi(b.z), w, false); w = __builtin_amdgcn_cvt_pk_fp8_f32(pg8::bf_lo(b.w), pg8::bf_hi(b.w), w, true); o.w = (unsigned)w;
;                             *(v4u*)((unsigned char*)q_Xs + (size_t)p * 1024 + 16 * lane) = o; } }
	v_lshlrev_b32_e32 v56, 16, v108
	v_and_b32_e32 v108, 0xffff0000, v108
	v_cvt_pk_fp8_f32 v54, v56, v108
	v_lshlrev_b32_e32 v56, 16, v109
	v_and_b32_e32 v109, 0xffff0000, v109
	v_cvt_pk_fp8_f32 v54, v56, v109 op_sel:[0,0,1]
	v_lshlrev_b32_e32 v56, 16, v110
	v_and_b32_e32 v110, 0xffff0000, v110
	v_cvt_pk_fp8_f32 v55, v56, v110
	v_lshlrev_b32_e32 v56, 16, v111
	v_and_b32_e32 v111, 0xffff0000, v111
	v_cvt_pk_fp8_f32 v55, v56, v111 op_sel:[0,0,1]
	global_store_dwordx4 v[50:51], v[52:55], off
	v_mov_b32_e32 v50, v38
	v_ashrrev_i32_e32 v51, 31, v50
	v_lshlrev_b64 v[50:51], 10, v[50:51]
	v_lshl_add_u64 v[50:51], s[26:27], 0, v[50:51]
	v_lshl_add_u64 v[50:51], v[50:51], 0, v[4:5]
	v_add_co_u32_e32 v50, vcc, 0x14500000, v50
	s_nop 1
	v_addc_co_u32_e32 v51, vcc, 0, v51, vcc
	v_mov_b32_e32 v52, 0
	v_mov_b32_e32 v53, 0
	v_mov_b32_e32 v54, 0
	v_mov_b32_e32 v55, 0
	s_waitcnt vmcnt(9)
	v_lshlrev_b32_e32 v56, 16, v112
	v_and_b32_e32 v112, 0xffff0000, v112
	v_cvt_pk_fp8_f32 v52, v56, v112
	v_lshlrev_b32_e32 v56, 16, v113
	v_and_b32_e32 v113, 0xffff0000, v113
	v_cvt_pk_fp8_f32 v52, v56, v113 op_sel:[0,0,1]
	v_lshlrev_b32_e32 v56, 16, v114
	v_and_b32_e32 v114, 0xffff0000, v114
	v_cvt_pk_fp8_f32 v53, v56, v114
	v_lshlrev_b32_e32 v56, 16, v115
	v_and_b32_e32 v115, 0xffff0000, v115
	v_cvt_pk_fp8_f32 v53, v56, v115 op_sel:[0,0,1]
	s_waitcnt vmcnt(8)
	v_lshlrev_b32_e32 v56, 16, v116
	v_and_b32_e32 v116, 0xffff0000, v116
	v_cvt_pk_fp8_f32 v54, v56, v116
	v_lshlrev_b32_e32 v56, 16, v117
	v_and_b32_e32 v117, 0xffff0000, v117
	v_cvt_pk_fp8_f32 v54, v56, v117 op_sel:[0,0,1]
	v_lshlrev_b32_e32 v56, 16, v118
	v_and_b32_e32 v118, 0xffff0000, v118
	v_cvt_pk_fp8_f32 v55, v56, v118
	v_lshlrev_b32_e32 v56, 16, v119
	v_and_b32_e32 v119, 0xffff0000, v119
	v_cvt_pk_fp8_f32 v55, v56, v119 op_sel:[0,0,1]
	global_store_dwordx4 v[50:51], v[52:55], off
	v_mov_b32_e32 v50, v39
	v_ashrrev_i32_e32 v51, 31, v50
	v_lshlrev_b64 v[50:51], 10, v[50:51]
	v_lshl_add_u64 v[50:51], s[26:27], 0, v[50:51]
	v_lshl_add_u64 v[50:51], v[50:51], 0, v[4:5]
	v_add_co_u32_e32 v50, vcc, 0x14500000, v50
	s_nop 1
	v_addc_co_u32_e32 v51, vcc, 0, v51, vcc
	v_mov_b32_e32 v52, 0
	v_mov_b32_e32 v53, 0
	v_mov_b32_e32 v54, 0
	v_mov_b32_e32 v55, 0
	s_waitcnt vmcnt(8)
	v_lshlrev_b32_e32 v56, 16, v120
	v_and_b32_e32 v120, 0xffff0000, v120
	v_cvt_pk_fp8_f32 v52, v56, v120
	v_lshlrev_b32_e32 v56, 16, v121
	v_and_b32_e32 v121, 0xffff0000, v121
	v_cvt_pk_fp8_f32 v52, v56, v121 op_sel:[0,0,1]
	v_lshlrev_b32_e32 v56, 16, v122
	v_and_b32_e32 v122, 0xffff0000, v122
	v_cvt_pk_fp8_f32 v53, v56, v122
	v_lshlrev_b32_e32 v56, 16, v123
	v_and_b32_e32 v123, 0xffff0000, v123
	v_cvt_pk_fp8_f32 v53, v56, v123 op_sel:[0,0,1]
	s_waitcnt vmcnt(7)
	v_lshlrev_b32_e32 v56, 16, v124
	v_and_b32_e32 v124, 0xffff0000, v124
	v_cvt_pk_fp8_f32 v54, v56, v124
	v_lshlrev_b32_e32 v56, 16, v125
	v_and_b32_e32 v125, 0xffff0000, v125
	v_cvt_pk_fp8_f32 v54, v56, v125 op_sel:[0,0,1]
	v_lshlrev_b32_e32 v56, 16, v126
	v_and_b32_e32 v126, 0xffff0000, v126
	v_cvt_pk_fp8_f32 v55, v56, v126
	v_lshlrev_b32_e32 v56, 16, v127
	v_and_b32_e32 v127, 0xffff0000, v127
	v_cvt_pk_fp8_f32 v55, v56, v127 op_sel:[0,0,1]
	global_store_dwordx4 v[50:51], v[52:55], off
	s_add_i32 s28, s16, 32
	s_ashr_i32 s29, s28, 31
	s_lshl_b64 s[38:39], s[28:29], 11
	s_add_u32 s38, s26, s38
	s_addc_u32 s39, s27, s39
	v_lshl_add_u64 v[48:49], s[38:39], 0, v[0:1]
	v_add_co_u32_e32 v48, vcc, s23, v48
	s_nop 1
	v_addc_co_u32_e32 v49, vcc, 0, v49, vcc
	global_load_dwordx4 v[64:67], v[48:49], off
	global_load_dwordx4 v[68:71], v[48:49], off offset:16
	s_add_i32 s28, s16, 36
	s_ashr_i32 s29, s28, 31
	s_lshl_b64 s[38:39], s[28:29], 11
	s_add_u32 s38, s26, s38
	s_addc_u32 s39, s27, s39
	v_lshl_add_u64 v[48:49], s[38:39], 0, v[0:1]
	v_add_co_u32_e32 v48, vcc, s23, v48
	s_nop 1
	v_addc_co_u32_e32 v49, vcc, 0, v49, vcc
	global_load_dwordx4 v[72:75], v[48:49], off
	global_load_dwordx4 v[76:79], v[48:49], off offset:16
	s_add_i32 s28, s16, 40
	s_ashr_i32 s29, s28, 31
	s_lshl_b64 s[38:39], s[28:29], 11
	s_add_u32 s38, s26, s38
	s_addc_u32 s39, s27, s39
	v_lshl_add_u64 v[48:49], s[38:39], 0, v[0:1]
	v_add_co_u32_e32 v48, vcc, s23, v48
	s_nop 1
	v_addc_co_u32_e32 v49, vcc, 0, v49, vcc
	global_load_dwordx4 v[80:83], v[48:49], off
	global_load_dwordx4 v[84:87], v[48:49], off offset:16
	s_add_i32 s28, s16, 44
	s_ashr_i32 s29, s28, 31
	s_lshl_b64 s[38:39], s[28:29], 11
	s_add_u32 s38, s26, s38
	s_addc_u32 s39, s27, s39
	v_lshl_add_u64 v[48:49], s[38:39], 0, v[0:1]
	v_add_co_u32_e32 v48, vcc, s23, v48
	s_nop 1
	v_addc_co_u32_e32 v49, vcc, 0, v49, vcc
	global_load_dwordx4 v[88:91], v[48:49], off
	global_load_dwordx4 v[92:95], v[48:49], off offset:16
	s_add_i32 s28, s16, 48
	s_ashr_i32 s29, s28, 31
	s_lshl_b64 s[38:39], s[28:29], 11
	s_add_u32 s38, s26, s38
	s_addc_u32 s39, s27, s39
	v_lshl_add_u64 v[48:49], s[38:39], 0, v[0:1]
	v_add_co_u32_e32 v48, vcc, s23, v48
	s_nop 1
	v_addc_co_u32_e32 v49, vcc, 0, v49, vcc
	global_load_dwordx4 v[96:99], v[48:49], off
	global_load_dwordx4 v[100:103], v[48:49], off offset:16
	s_add_i32 s28, s16, 52
	s_ashr_i32 s29, s28, 31
	s_lshl_b64 s[38:39], s[28:29], 11
	s_add_u32 s38, s26, s38
	s_addc_u32 s39, s27, s39
	v_lshl_add_u64 v[48:49], s[38:39], 0, v[0:1]
	v_add_co_u32_e32 v48, vcc, s23, v48
	s_nop 1
	v_addc_co_u32_e32 v49, vcc, 0, v49, vcc
	global_load_dwordx4 v[104:107], v[48:49], off
	global_load_dwordx4 v[108:111], v[48:49], off offset:16
	s_add_i32 s28, s16, 56
	s_ashr_i32 s29, s28, 31
	s_lshl_b64 s[38:39], s[28:29], 11
	s_add_u32 s38, s26, s38
	s_addc_u32 s39, s27, s39
	v_lshl_add_u64 v[48:49], s[38:39], 0, v[0:1]
	v_add_co_u32_e32 v48, vcc, s23, v48
	s_nop 1
	v_addc_co_u32_e32 v49, vcc, 0, v49, vcc
	global_load_dwordx4 v[112:115], v[48:49], off
	global_load_dwordx4 v[116:119], v[48:49], off offset:16
	s_add_i32 s28, s16, 60
	s_ashr_i32 s29, s28, 31
	s_lshl_b64 s[38:39], s[28:29], 11
	s_add_u32 s38, s26, s38
	s_addc_u32 s39, s27, s39
	v_lshl_add_u64 v[48:49], s[38:39], 0, v[0:1]
	v_add_co_u32_e32 v48, vcc, s23, v48
	s_nop 1
	v_addc_co_u32_e32 v49, vcc, 0, v49, vcc
	global_load_dwordx4 v[120:123], v[48:49], off
	global_load_dwordx4 v[124:127], v[48:49], off offset:16
	v_mov_b32_e32 v50, v40
	v_ashrrev_i32_e32 v51, 31, v50
	v_lshlrev_b64 v[50:51], 10, v[50:51]
	v_lshl_add_u64 v[50:51], s[26:27], 0, v[50:51]
	v_lshl_add_u64 v[50:51], v[50:51], 0, v[4:5]
	v_add_co_u32_e32 v50, vcc, 0x14500000, v50
	s_nop 1
	v_addc_co_u32_e32 v51, vcc, 0, v51, vcc
	v_mov_b32_e32 v52, 0
	v_mov_b32_e32 v53, 0
	v_mov_b32_e32 v54, 0
	v_mov_b32_e32 v55, 0
	s_waitcnt vmcnt(15)
; __device__ __forceinline__ float bf_lo(unsigned w) { return __uint_as_float(w << 16); }
; __device__ __forceinline__ float bf_hi(unsigned w) { return __uint_as_float(w & 0xffff0000u); }
; #define LAS __attribute__((address_space(3)))
; template <int l, int SEL> __device__ __forceinline__ void layer_body(const Args& args, LAS unsigned char* ldsp, unsigned char* lds, const int G, const int bx, const int vcu, const int wv) {
;     ...
;                     for (int sidx = wave; sidx < 128; sidx += NWAVES) { const int p = ((LAS int*)ldsp)[64 + sidx]; const int tk = tb + (sidx >> 1);
;                         { const v4u a = *(const v4u*)(q_hb + (size_t)tk * 1024 + 16 * lane), b = *(const v4u*)(q_hb + (size_t)tk * 1024 + 16 * lane + 8); v4u o; int w;
;                             w = 0; w = __builtin_amdgcn_cvt_pk_fp8_f32(pg8::bf_lo(a.x), pg8::bf_hi(a.x), w, false); w = __builtin_amdgcn_cvt_pk_fp8_f32(pg8::bf_lo(a.y), pg8::bf_hi(a.y), w, true); o.x = (unsigned)w;
;                             w = 0; w = __builtin_amdgcn_cvt_pk_fp8_f32(pg8::bf_lo(a.z), pg8::bf_hi(a.z), w, false); w = __builtin_amdgcn_cvt_pk_fp8_f32(pg8::bf_lo(a.w), pg8::bf_hi(a.w), w, true); o.y = (unsigned)w;
;                             w = 0; w = __builtin_amdgcn_cvt_pk_fp8_f32(pg8::bf_lo(b.x), pg8::bf_hi(b.x), w, false); w = __builtin_amdgcn_cvt_pk_fp8_f32(pg8::bf_lo(b.y), pg8::bf_hi(b.y), w, true); o.z = (unsigned)w;
;                             w = 0; w = __builtin_amdgcn_cvt_pk_fp8_f32(pg8::bf_lo(b.z), pg8::bf_hi(b.z), w, false); w = __builtin_amdgcn_cvt_pk_fp8_f32(pg8::bf_lo(b.w), pg8::bf_hi(b.w), w, true); o.w = (unsigned)w;
;                             *(v4u*)((unsigned char*)q_Xs + (size_t)p * 1024 + 16 * lane) = o; } }
	v_lshlrev_b32_e32 v56, 16, v64
	v_and_b32_e32 v64, 0xffff0000, v64
	v_cvt_pk_fp8_f32 v52, v56, v64
	v_lshlrev_b32_e32 v56, 16, v65
	v_and_b32_e32 v65, 0xffff0000, v65
	v_cvt_pk_fp8_f32 v52, v56, v65 op_sel:[0,0,1]
	v_lshlrev_b32_e32 v56, 16, v66
	v_and_b32_e32 v66, 0xffff0000, v66
	v_cvt_pk_fp8_f32 v53, v56, v66
	v_lshlrev_b32_e32 v56, 16, v67
	v_and_b32_e32 v67, 0xffff0000, v67
	v_cvt_pk_fp8_f32 v53, v56, v67 op_sel:[0,0,1]
	s_waitcnt vmcnt(14)
	v_lshlrev_b32_e32 v56, 16, v68
	v_and_b32_e32 v68, 0xffff0000, v68
	v_cvt_pk_fp8_f32 v54, v56, v68
	v_lshlrev_b32_e32 v56, 16, v69
	v_and_b32_e32 v69, 0xffff0000, v69
	v_cvt_pk_fp8_f32 v54, v56, v69 op_sel:[0,0,1]
	v_lshlrev_b32_e32 v56, 16, v70
	v_and_b32_e32 v70, 0xffff0000, v70
	v_cvt_pk_fp8_f32 v55, v56, v70
	v_lshlrev_b32_e32 v56, 16, v71
	v_and_b32_e32 v71, 0xffff0000, v71
	v_cvt_pk_fp8_f32 v55, v56, v71 op_sel:[0,0,1]
	global_store_dwordx4 v[50:51], v[52:55], off
	v_mov_b32_e32 v50, v41
	v_ashrrev_i32_e32 v51, 31, v50
	v_lshlrev_b64 v[50:51], 10, v[50:51]
	v_lshl_add_u64 v[50:51], s[26:27], 0, v[50:51]
	v_lshl_add_u64 v[50:51], v[50:51], 0, v[4:5]
	v_add_co_u32_e32 v50, vcc, 0x14500000, v50
	s_nop 1
	v_addc_co_u32_e32 v51, vcc, 0, v51, vcc
	v_mov_b32_e32 v52, 0
	v_mov_b32_e32 v53, 0
	v_mov_b32_e32 v54, 0
	v_mov_b32_e32 v55, 0
	s_waitcnt vmcnt(14)
	v_lshlrev_b32_e32 v56, 16, v72
	v_and_b32_e32 v72, 0xffff0000, v72
	v_cvt_pk_fp8_f32 v52, v56, v72
	v_lshlrev_b32_e32 v56, 16, v73
	v_and_b32_e32 v73, 0xffff0000, v73
	v_cvt_pk_fp8_f32 v52, v56, v73 op_sel:[0,0,1]
	v_lshlrev_b32_e32 v56, 16, v74
	v_and_b32_e32 v74, 0xffff0000, v74
	v_cvt_pk_fp8_f32 v53, v56, v74
	v_lshlrev_b32_e32 v56, 16, v75
	v_and_b32_e32 v75, 0xffff0000, v75
	v_cvt_pk_fp8_f32 v53, v56, v75 op_sel:[0,0,1]
	s_waitcnt vmcnt(13)
	v_lshlrev_b32_e32 v56, 16, v76
	v_and_b32_e32 v76, 0xffff0000, v76
	v_cvt_pk_fp8_f32 v54, v56, v76
	v_lshlrev_b32_e32 v56, 16, v77
	v_and_b32_e32 v77, 0xffff0000, v77
	v_cvt_pk_fp8_f32 v54, v56, v77 op_sel:[0,0,1]
	v_lshlrev_b32_e32 v56, 16, v78
	v_and_b32_e32 v78, 0xffff0000, v78
	v_cvt_pk_fp8_f32 v55, v56, v78
	v_lshlrev_b32_e32 v56, 16, v79
	v_and_b32_e32 v79, 0xffff0000, v79
	v_cvt_pk_fp8_f32 v55, v56, v79 op_sel:[0,0,1]
	global_store_dwordx4 v[50:51], v[52:55], off
	v_mov_b32_e32 v50, v42
	v_ashrrev_i32_e32 v51, 31, v50
	v_lshlrev_b64 v[50:51], 10, v[50:51]
	v_lshl_add_u64 v[50:51], s[26:27], 0, v[50:51]
	v_lshl_add_u64 v[50:51], v[50:51], 0, v[4:5]
	v_add_co_u32_e32 v50, vcc, 0x14500000, v50
	s_nop 1
	v_addc_co_u32_e32 v51, vcc, 0, v51, vcc
	v_mov_b32_e32 v52, 0
	v_mov_b32_e32 v53, 0
	v_mov_b32_e32 v54, 0
	v_mov_b32_e32 v55, 0
	s_waitcnt vmcnt(13)
	v_lshlrev_b32_e32 v56, 16, v80
	v_and_b32_e32 v80, 0xffff0000, v80
	v_cvt_pk_fp8_f32 v52, v56, v80
	v_lshlrev_b32_e32 v56, 16, v81
	v_and_b32_e32 v81, 0xffff0000, v81
	v_cvt_pk_fp8_f32 v52, v56, v81 op_sel:[0,0,1]
	v_lshlrev_b32_e32 v56, 16, v82
	v_and_b32_e32 v82, 0xffff0000, v82
	v_cvt_pk_fp8_f32 v53, v56, v82
	v_lshlrev_b32_e32 v56, 16, v83
	v_and_b32_e32 v83, 0xffff0000, v83
	v_cvt_pk_fp8_f32 v53, v56, v83 op_sel:[0,0,1]
	s_waitcnt vmcnt(12)
	v_lshlrev_b32_e32 v56, 16, v84
	v_and_b32_e32 v84, 0xffff0000, v84
	v_cvt_pk_fp8_f32 v54, v56, v84
	v_lshlrev_b32_e32 v56, 16, v85
	v_and_b32_e32 v85, 0xffff0000, v85
	v_cvt_pk_fp8_f32 v54, v56, v85 op_sel:[0,0,1]
	v_lshlrev_b32_e32 v56, 16, v86
	v_and_b32_e32 v86, 0xffff0000, v86
	v_cvt_pk_fp8_f32 v55, v56, v86
	v_lshlrev_b32_e32 v56, 16, v87
	v_and_b32_e32 v87, 0xffff0000, v87
	v_cvt_pk_fp8_f32 v55, v56, v87 op_sel:[0,0,1]
	global_store_dwordx4 v[50:51], v[52:55], off
	v_mov_b32_e32 v50, v43
	v_ashrrev_i32_e32 v51, 31, v50
	v_lshlrev_b64 v[50:51], 10, v[50:51]
	v_lshl_add_u64 v[50:51], s[26:27], 0, v[50:51]
	v_lshl_add_u64 v[50:51], v[50:51], 0, v[4:5]
	v_add_co_u32_e32 v50, vcc, 0x14500000, v50
	s_nop 1
	v_addc_co_u32_e32 v51, vcc, 0, v51, vcc
	v_mov_b32_e32 v52, 0
	v_mov_b32_e32 v53, 0
	v_mov_b32_e32 v54, 0
	v_mov_b32_e32 v55, 0
	s_waitcnt vmcnt(12)
	v_lshlrev_b32_e32 v56, 16, v88
	v_and_b32_e32 v88, 0xffff0000, v88
	v_cvt_pk_fp8_f32 v52, v56, v88
	v_lshlrev_b32_e32 v56, 16, v89
	v_and_b32_e32 v89, 0xffff0000, v89
	v_cvt_pk_fp8_f32 v52, v56, v89 op_sel:[0,0,1]
	v_lshlrev_b32_e32 v56, 16, v90
	v_and_b32_e32 v90, 0xffff0000, v90
	v_cvt_pk_fp8_f32 v53, v56, v90
	v_lshlrev_b32_e32 v56, 16, v91
	v_and_b32_e32 v91, 0xffff0000, v91
	v_cvt_pk_fp8_f32 v53, v56, v91 op_sel:[0,0,1]
	s_waitcnt vmcnt(11)
	v_lshlrev_b32_e32 v56, 16, v92
	v_and_b32_e32 v92, 0xffff0000, v92
	v_cvt_pk_fp8_f32 v54, v56, v92
	v_lshlrev_b32_e32 v56, 16, v93
	v_and_b32_e32 v93, 0xffff0000, v93
	v_cvt_pk_fp8_f32 v54, v56, v93 op_sel:[0,0,1]
	v_lshlrev_b32_e32 v56, 16, v94
	v_and_b32_e32 v94, 0xffff0000, v94
	v_cvt_pk_fp8_f32 v55, v56, v94
	v_lshlrev_b32_e32 v56, 16, v95
	v_and_b32_e32 v95, 0xffff0000, v95
	v_cvt_pk_fp8_f32 v55, v56, v95 op_sel:[0,0,1]
	global_store_dwordx4 v[50:51], v[52:55], off
	v_mov_b32_e32 v50, v44
	v_ashrrev_i32_e32 v51, 31, v50
	v_lshlrev_b64 v[50:51], 10, v[50:51]
	v_lshl_add_u64 v[50:51], s[26:27], 0, v[50:51]
	v_lshl_add_u64 v[50:51], v[50:51], 0, v[4:5]
	v_add_co_u32_e32 v50, vcc, 0x14500000, v50
	s_nop 1
	v_addc_co_u32_e32 v51, vcc, 0, v51, vcc
	v_mov_b32_e32 v52, 0
	v_mov_b32_e32 v53, 0
	v_mov_b32_e32 v54, 0
	v_mov_b32_e32 v55, 0
	s_waitcnt vmcnt(11)
; __device__ __forceinline__ float bf_lo(unsigned w) { return __uint_as_float(w << 16); }
; __device__ __forceinline__ float bf_hi(unsigned w) { return __uint_as_float(w & 0xffff0000u); }
; #define LAS __attribute__((address_space(3)))
; template <int l, int SEL> __device__ __forceinline__ void layer_body(const Args& args, LAS unsigned char* ldsp, unsigned char* lds, const int G, const int bx, const int vcu, const int wv) {
;     ...
;                     for (int sidx = wave; sidx < 128; sidx += NWAVES) { const int p = ((LAS int*)ldsp)[64 + sidx]; const int tk = tb + (sidx >> 1);
;                         { const v4u a = *(const v4u*)(q_hb + (size_t)tk * 1024 + 16 * lane), b = *(const v4u*)(q_hb + (size_t)tk * 1024 + 16 * lane + 8); v4u o; int w;
;                             w = 0; w = __builtin_amdgcn_cvt_pk_fp8_f32(pg8::bf_lo(a.x), pg8::bf_hi(a.x), w, false); w = __builtin_amdgcn_cvt_pk_fp8_f32(pg8::bf_lo(a.y), pg8::bf_hi(a.y), w, true); o.x = (unsigned)w;
;                             w = 0; w = __builtin_amdgcn_cvt_pk_fp8_f32(pg8::bf_lo(a.z), pg8::bf_hi(a.z), w, false); w = __builtin_amdgcn_cvt_pk_fp8_f32(pg8::bf_lo(a.w), pg8::bf_hi(a.w), w, true); o.y = (unsigned)w;
;                             w = 0; w = __builtin_amdgcn_cvt_pk_fp8_f32(pg8::bf_lo(b.x), pg8::bf_hi(b.x), w, false); w = __builtin_amdgcn_cvt_pk_fp8_f32(pg8::bf_lo(b.y), pg8::bf_hi(b.y), w, true); o.z = (unsigned)w;
;                             w = 0; w = __builtin_amdgcn_cvt_pk_fp8_f32(pg8::bf_lo(b.z), pg8::bf_hi(b.z), w, false); w = __builtin_amdgcn_cvt_pk_fp8_f32(pg8::bf_lo(b.w), pg8::bf_hi(b.w), w, true); o.w = (unsigned)w;
;                             *(v4u*)((unsigned char*)q_Xs + (size_t)p * 1024 + 16 * lane) = o; } }
;                     __syncthreads();
	v_lshlrev_b32_e32 v56, 16, v96
	v_and_b32_e32 v96, 0xffff0000, v96
	v_cvt_pk_fp8_f32 v52, v56, v96
	v_lshlrev_b32_e32 v56, 16, v97
	v_and_b32_e32 v97, 0xffff0000, v97
	v_cvt_pk_fp8_f32 v52, v56, v97 op_sel:[0,0,1]
	v_lshlrev_b32_e32 v56, 16, v98
	v_and_b32_e32 v98, 0xffff0000, v98
	v_cvt_pk_fp8_f32 v53, v56, v98
	v_lshlrev_b32_e32 v56, 16, v99
	v_and_b32_e32 v99, 0xffff0000, v99
	v_cvt_pk_fp8_f32 v53, v56, v99 op_sel:[0,0,1]
	s_waitcnt vmcnt(10)
	v_lshlrev_b32_e32 v56, 16, v100
	v_and_b32_e32 v100, 0xffff0000, v100
	v_cvt_pk_fp8_f32 v54, v56, v100
	v_lshlrev_b32_e32 v56, 16, v101
	v_and_b32_e32 v101, 0xffff0000, v101
	v_cvt_pk_fp8_f32 v54, v56, v101 op_sel:[0,0,1]
	v_lshlrev_b32_e32 v56, 16, v102
	v_and_b32_e32 v102, 0xffff0000, v102
	v_cvt_pk_fp8_f32 v55, v56, v102
	v_lshlrev_b32_e32 v56, 16, v103
	v_and_b32_e32 v103, 0xffff0000, v103
	v_cvt_pk_fp8_f32 v55, v56, v103 op_sel:[0,0,1]
	global_store_dwordx4 v[50:51], v[52:55], off
	v_mov_b32_e32 v50, v45
	v_ashrrev_i32_e32 v51, 31, v50
	v_lshlrev_b64 v[50:51], 10, v[50:51]
	v_lshl_add_u64 v[50:51], s[26:27], 0, v[50:51]
	v_lshl_add_u64 v[50:51], v[50:51], 0, v[4:5]
	v_add_co_u32_e32 v50, vcc, 0x14500000, v50
	s_nop 1
	v_addc_co_u32_e32 v51, vcc, 0, v51, vcc
	v_mov_b32_e32 v52, 0
	v_mov_b32_e32 v53, 0
	v_mov_b32_e32 v54, 0
	v_mov_b32_e32 v55, 0
	s_waitcnt vmcnt(10)
	v_lshlrev_b32_e32 v56, 16, v104
	v_and_b32_e32 v104, 0xffff0000, v104
	v_cvt_pk_fp8_f32 v52, v56, v104
	v_lshlrev_b32_e32 v56, 16, v105
	v_and_b32_e32 v105, 0xffff0000, v105
	v_cvt_pk_fp8_f32 v52, v56, v105 op_sel:[0,0,1]
	v_lshlrev_b32_e32 v56, 16, v106
	v_and_b32_e32 v106, 0xffff0000, v106
	v_cvt_pk_fp8_f32 v53, v56, v106
	v_lshlrev_b32_e32 v56, 16, v107
	v_and_b32_e32 v107, 0xffff0000, v107
	v_cvt_pk_fp8_f32 v53, v56, v107 op_sel:[0,0,1]
	s_waitcnt vmcnt(9)
	v_lshlrev_b32_e32 v56, 16, v108
	v_and_b32_e32 v108, 0xffff0000, v108
	v_cvt_pk_fp8_f32 v54, v56, v108
	v_lshlrev_b32_e32 v56, 16, v109
	v_and_b32_e32 v109, 0xffff0000, v109
	v_cvt_pk_fp8_f32 v54, v56, v109 op_sel:[0,0,1]
	v_lshlrev_b32_e32 v56, 16, v110
	v_and_b32_e32 v110, 0xffff0000, v110
	v_cvt_pk_fp8_f32 v55, v56, v110
	v_lshlrev_b32_e32 v56, 16, v111
	v_and_b32_e32 v111, 0xffff0000, v111
	v_cvt_pk_fp8_f32 v55, v56, v111 op_sel:[0,0,1]
	global_store_dwordx4 v[50:51], v[52:55], off
	v_mov_b32_e32 v50, v46
	v_ashrrev_i32_e32 v51, 31, v50
	v_lshlrev_b64 v[50:51], 10, v[50:51]
	v_lshl_add_u64 v[50:51], s[26:27], 0, v[50:51]
	v_lshl_add_u64 v[50:51], v[50:51], 0, v[4:5]
	v_add_co_u32_e32 v50, vcc, 0x14500000, v50
	s_nop 1
	v_addc_co_u32_e32 v51, vcc, 0, v51, vcc
	v_mov_b32_e32 v52, 0
	v_mov_b32_e32 v53, 0
	v_mov_b32_e32 v54, 0
	v_mov_b32_e32 v55, 0
	s_waitcnt vmcnt(9)
	v_lshlrev_b32_e32 v56, 16, v112
	v_and_b32_e32 v112, 0xffff0000, v112
	v_cvt_pk_fp8_f32 v52, v56, v112
	v_lshlrev_b32_e32 v56, 16, v113
	v_and_b32_e32 v113, 0xffff0000, v113
	v_cvt_pk_fp8_f32 v52, v56, v113 op_sel:[0,0,1]
	v_lshlrev_b32_e32 v56, 16, v114
	v_and_b32_e32 v114, 0xffff0000, v114
	v_cvt_pk_fp8_f32 v53, v56, v114
	v_lshlrev_b32_e32 v56, 16, v115
	v_and_b32_e32 v115, 0xffff0000, v115
	v_cvt_pk_fp8_f32 v53, v56, v115 op_sel:[0,0,1]
	s_waitcnt vmcnt(8)
	v_lshlrev_b32_e32 v56, 16, v116
	v_and_b32_e32 v116, 0xffff0000, v116
	v_cvt_pk_fp8_f32 v54, v56, v116
	v_lshlrev_b32_e32 v56, 16, v117
	v_and_b32_e32 v117, 0xffff0000, v117
	v_cvt_pk_fp8_f32 v54, v56, v117 op_sel:[0,0,1]
	v_lshlrev_b32_e32 v56, 16, v118
	v_and_b32_e32 v118, 0xffff0000, v118
	v_cvt_pk_fp8_f32 v55, v56, v118
	v_lshlrev_b32_e32 v56, 16, v119
	v_and_b32_e32 v119, 0xffff0000, v119
	v_cvt_pk_fp8_f32 v55, v56, v119 op_sel:[0,0,1]
	global_store_dwordx4 v[50:51], v[52:55], off
	v_mov_b32_e32 v50, v47
	v_ashrrev_i32_e32 v51, 31, v50
	v_lshlrev_b64 v[50:51], 10, v[50:51]
	v_lshl_add_u64 v[50:51], s[26:27], 0, v[50:51]
	v_lshl_add_u64 v[50:51], v[50:51], 0, v[4:5]
	v_add_co_u32_e32 v50, vcc, 0x14500000, v50
	s_nop 1
	v_addc_co_u32_e32 v51, vcc, 0, v51, vcc
	v_mov_b32_e32 v52, 0
	v_mov_b32_e32 v53, 0
	v_mov_b32_e32 v54, 0
	v_mov_b32_e32 v55, 0
	s_waitcnt vmcnt(8)
	v_lshlrev_b32_e32 v56, 16, v120
	v_and_b32_e32 v120, 0xffff0000, v120
	v_cvt_pk_fp8_f32 v52, v56, v120
	v_lshlrev_b32_e32 v56, 16, v121
	v_and_b32_e32 v121, 0xffff0000, v121
	v_cvt_pk_fp8_f32 v52, v56, v121 op_sel:[0,0,1]
	v_lshlrev_b32_e32 v56, 16, v122
	v_and_b32_e32 v122, 0xffff0000, v122
	v_cvt_pk_fp8_f32 v53, v56, v122
	v_lshlrev_b32_e32 v56, 16, v123
	v_and_b32_e32 v123, 0xffff0000, v123
	v_cvt_pk_fp8_f32 v53, v56, v123 op_sel:[0,0,1]
	s_waitcnt vmcnt(7)
	v_lshlrev_b32_e32 v56, 16, v124
	v_and_b32_e32 v124, 0xffff0000, v124
	v_cvt_pk_fp8_f32 v54, v56, v124
	v_lshlrev_b32_e32 v56, 16, v125
	v_and_b32_e32 v125, 0xffff0000, v125
	v_cvt_pk_fp8_f32 v54, v56, v125 op_sel:[0,0,1]
	v_lshlrev_b32_e32 v56, 16, v126
	v_and_b32_e32 v126, 0xffff0000, v126
	v_cvt_pk_fp8_f32 v55, v56, v126
	v_lshlrev_b32_e32 v56, 16, v127
	v_and_b32_e32 v127, 0xffff0000, v127
	v_cvt_pk_fp8_f32 v55, v56, v127 op_sel:[0,0,1]
	global_store_dwordx4 v[50:51], v[52:55], off
	s_branch .LBB0_1967
